# cscan: scan slot = 2*bid + wave so both v-halves of a chain share one workgroup (L2 reuse of operand tiles)
# speedup vs baseline: 1.0180x; 1.0119x over previous
.LBB0_972:
	s_andn2_b64 vcc, exec, s[0:1]
	s_cbranch_vccnz .LBB0_1156
	v_mov_b32_e32 v150, v234
	v_readlane_b32 s0, v253, 7
	v_readlane_b32 s1, v253, 8
	s_cmp_lt_i32 s62, 2
	s_nop 0
	v_writelane_b32 v253, s1, 8
	v_writelane_b32 v253, s0, 7
	s_mov_b64 s[0:1], -1
	s_cbranch_scc0 .LBB0_995
	s_setprio 3
	v_readlane_b32 s0, v253, 61
	v_readlane_b32 s1, v253, 7
	v_writelane_b32 v255, s62, 8
	v_mov_b32_e32 v0, s0
	ds_read_b64 v[2:3], v0
	v_readlane_b32 s0, v253, 8
	s_lshl_b32 s0, s1, 1
	s_add_i32 s5, s0, s62
	s_cmpk_gt_i32 s5, 0x8ff
	s_waitcnt lgkmcnt(0)
	v_readfirstlane_b32 s0, v2
	v_readfirstlane_b32 s1, v3
	s_cbranch_scc1 .LBB0_994
	s_add_u32 s2, s0, 0x5c400000
	v_writelane_b32 v255, s2, 13
	s_addc_u32 s2, s1, 0
	v_writelane_b32 v255, s2, 14
	s_add_u32 s2, s0, 0x72e00000
	v_writelane_b32 v255, s2, 6
	s_addc_u32 s2, s1, 0
	s_add_u32 s27, s0, 0x74e00000
	s_addc_u32 s23, s1, 0
	v_writelane_b32 v255, s2, 0
	s_add_u32 s0, s0, 0x25400000
	v_writelane_b32 v255, s0, 15
	s_addc_u32 s0, s1, 0
	v_writelane_b32 v255, s0, 16
	v_readlane_b32 s0, v253, 8
	s_lshl_b32 s8, s0, 1
	v_readlane_b32 s0, v255, 8
	s_mul_i32 s0, s0, 0xb800
	s_add_i32 s22, s0, 0
	v_readlane_b32 s0, v254, 60
	v_readlane_b32 s1, v254, 61
	s_lshl_b32 s0, s0, 1
	s_mov_b32 s1, s17
	v_writelane_b32 v255, s0, 17
	v_ashrrev_i32_e32 v2, 5, v150
	v_lshlrev_b32_e32 v5, 9, v2
	v_writelane_b32 v255, s1, 18
	s_add_i32 s0, s22, 0x2000
	v_writelane_b32 v255, s0, 4
	s_add_i32 s0, s22, 0x3000
	v_writelane_b32 v255, s0, 5
	s_add_i32 s0, s22, 0x4000
	v_writelane_b32 v255, s0, 9
	s_add_i32 s0, s22, 0x5000
	v_writelane_b32 v255, s0, 10
	s_add_i32 s0, s22, 0x5800
	v_writelane_b32 v255, s0, 11
	s_add_i32 s0, s22, 0x6c00
	v_writelane_b32 v255, s0, 19
	s_add_i32 s0, s22, 0x7c00
	v_writelane_b32 v255, s0, 20
	s_add_i32 s0, s22, 0x8c00
	v_writelane_b32 v255, s0, 21
	s_add_i32 s0, s22, 0x9c00
	v_writelane_b32 v255, s0, 22
	s_add_i32 s0, s22, 0x6000
	v_writelane_b32 v255, s0, 23
	s_add_i32 s0, s22, 0x7000
	v_writelane_b32 v255, s0, 24
	s_add_i32 s0, s22, 0x8000
	v_writelane_b32 v255, s0, 25
	s_add_i32 s0, s22, 0x9000
	v_writelane_b32 v255, s0, 26
	s_add_i32 s0, s22, 0xa000
	v_writelane_b32 v255, s0, 27
	s_add_i32 s0, s22, 0x6400
	v_writelane_b32 v255, s0, 28
	s_add_i32 s0, s22, 0x7400
	v_writelane_b32 v255, s0, 29
	s_add_i32 s0, s22, 0x8400
	v_writelane_b32 v255, s0, 30
	s_add_i32 s0, s22, 0x9400
	v_writelane_b32 v255, s0, 31
	s_add_i32 s0, s22, 0xa400
	v_writelane_b32 v255, s0, 32
	s_add_i32 s0, s22, 0x6800
	v_writelane_b32 v255, s0, 33
	s_add_i32 s0, s22, 0x7800
	v_writelane_b32 v255, s0, 34
	s_add_i32 s0, s22, 0x8800
	v_writelane_b32 v255, s0, 35
	s_add_i32 s0, s22, 0x9800
	v_writelane_b32 v255, s0, 36
	s_add_i32 s0, s22, 0xa800
	v_writelane_b32 v255, s0, 37
	s_add_i32 s0, s22, 0xac00
	v_writelane_b32 v255, s0, 38
	s_add_i32 s0, s22, 0xb000
	v_writelane_b32 v255, s0, 39
	s_add_i32 s0, s22, 0xb400
	v_lshlrev_b32_e32 v6, 5, v150
	s_movk_i32 s4, 0x180
	v_writelane_b32 v255, s0, 40
	v_and_or_b32 v5, v6, s4, v5
	s_add_i32 s4, s22, 0x400
	v_writelane_b32 v255, s4, 2
	s_add_i32 s4, s22, 0x1400
	v_writelane_b32 v255, s4, 3
	s_add_i32 s4, s22, 0x2400
	v_writelane_b32 v255, s4, 41
	s_add_i32 s4, s22, 0x3400
	v_writelane_b32 v255, s4, 42
	s_add_i32 s4, s22, 0x4400
	v_writelane_b32 v255, s4, 43
	s_add_i32 s4, s22, 0x800
	v_writelane_b32 v255, s4, 44
	s_add_i32 s4, s22, 0x1800
	v_writelane_b32 v255, s4, 45
	s_add_i32 s4, s22, 0x2800
	v_writelane_b32 v255, s4, 46
	s_add_i32 s4, s22, 0x3800
	v_writelane_b32 v255, s4, 47
	s_add_i32 s4, s22, 0x4800
	v_writelane_b32 v255, s4, 48
	s_add_i32 s4, s22, 0xc00
	v_writelane_b32 v255, s4, 49
	s_add_i32 s4, s22, 0x1c00
	v_writelane_b32 v255, s4, 50
	s_add_i32 s4, s22, 0x2c00
	v_writelane_b32 v255, s4, 51
	s_add_i32 s4, s22, 0x3c00
	v_writelane_b32 v255, s4, 52
	s_add_i32 s4, s22, 0x4c00
	v_and_b32_e32 v0, 31, v150
	s_add_i32 s19, s22, 0x1000
	s_add_i32 s6, s22, 0x5c00
	v_lshlrev_b32_e32 v7, 3, v150
	v_lshlrev_b32_e32 v8, 1, v150
	v_writelane_b32 v255, s4, 53
	s_add_i32 s4, s22, 0x5400
	s_addk_i32 s8, 0xff00
	v_lshlrev_b32_e32 v151, 6, v0
	v_lshlrev_b32_e32 v152, 2, v2
	v_lshlrev_b32_e32 v3, 7, v0
	v_lshlrev_b32_e32 v160, 4, v2
	v_and_b32_e32 v7, 24, v7
	v_and_b32_e32 v8, 32, v8
	v_writelane_b32 v255, s4, 54
	s_cmpk_gt_i32 s5, 0xff
	v_add_u32_e32 v4, v3, v160
	v_or_b32_e32 v161, 1, v152
	v_or_b32_e32 v162, 2, v152
	v_or_b32_e32 v163, 3, v152
	v_add_u32_e32 v164, 8, v152
	v_add_u32_e32 v165, 9, v152
	v_add_u32_e32 v166, 10, v152
	v_add_u32_e32 v167, 11, v152
	v_add_u32_e32 v168, 16, v152
	v_add_u32_e32 v169, 17, v152
	v_add_u32_e32 v170, 18, v152
	v_add_u32_e32 v171, 19, v152
	v_add_u32_e32 v172, 24, v152
	v_add_u32_e32 v173, 25, v152
	v_add_u32_e32 v174, 26, v152
	v_add_u32_e32 v175, 27, v152
	v_or3_b32 v5, v5, v8, v7
	v_add_u32_e32 v3, s22, v3
	v_lshlrev_b32_e32 v2, 3, v2
	v_add_u32_e32 v6, s22, v151
	v_writelane_b32 v255, s6, 55
	s_cselect_b32 s4, s8, 0x900
	v_ashrrev_i32_e32 v153, 31, v152
	v_cmp_lt_i32_e64 s[0:1], v152, v0
	v_cmp_lt_i32_e64 s[2:3], v161, v0
	v_cmp_lt_i32_e64 s[34:35], v162, v0
	v_cmp_lt_i32_e64 s[36:37], v163, v0
	v_cmp_lt_i32_e64 s[38:39], v164, v0
	v_cmp_lt_i32_e64 s[40:41], v165, v0
	v_cmp_lt_i32_e64 s[42:43], v166, v0
	v_cmp_lt_i32_e64 s[44:45], v167, v0
	v_cmp_lt_i32_e64 s[46:47], v168, v0
	v_cmp_lt_i32_e64 s[48:49], v169, v0
	v_cmp_lt_i32_e64 s[50:51], v170, v0
	v_cmp_lt_i32_e64 s[52:53], v171, v0
	v_cmp_lt_i32_e64 s[54:55], v172, v0
	v_cmp_lt_i32_e64 s[56:57], v173, v0
	v_cmp_lt_i32_e64 s[58:59], v174, v0
	v_add_u32_e32 v176, s22, v5
	v_sub_u32_e32 v177, 31, v152
	v_sub_u32_e32 v178, 31, v161
	v_sub_u32_e32 v179, 31, v162
	v_sub_u32_e32 v180, 31, v163
	v_sub_u32_e32 v181, 23, v152
	v_sub_u32_e32 v182, 22, v152
	v_sub_u32_e32 v183, 21, v152
	v_sub_u32_e32 v184, 20, v152
	v_sub_u32_e32 v185, 15, v152
	v_sub_u32_e32 v186, 14, v152
	v_sub_u32_e32 v187, 13, v152
	v_sub_u32_e32 v188, 12, v152
	v_sub_u32_e32 v189, 7, v152
	v_sub_u32_e32 v190, 6, v152
	v_sub_u32_e32 v191, 5, v152
	v_sub_u32_e32 v192, 4, v152
	v_add_u32_e32 v193, s6, v5
	v_writelane_b32 v255, s4, 56
	v_lshlrev_b32_e32 v154, 2, v0
	v_add_u32_e32 v194, s22, v4
	v_add_u32_e32 v195, v3, v2
	v_add_u32_e32 v196, v6, v2
	v_cmp_lt_i32_e64 s[60:61], v175, v0
	v_cmp_gt_i32_e64 s[62:63], v152, v0
	v_cmp_gt_i32_e64 s[64:65], v162, v0
	v_cmp_gt_i32_e64 s[66:67], v163, v0
	v_cmp_gt_i32_e64 s[68:69], v164, v0
	v_cmp_gt_i32_e64 s[70:71], v165, v0
	v_cmp_gt_i32_e64 s[72:73], v166, v0
	v_cmp_gt_i32_e64 s[74:75], v167, v0
	v_cmp_gt_i32_e64 s[76:77], v168, v0
	v_cmp_gt_i32_e64 s[78:79], v169, v0
	v_cmp_gt_i32_e64 s[80:81], v170, v0
	v_cmp_gt_i32_e64 s[82:83], v171, v0
	v_cmp_gt_i32_e64 s[84:85], v172, v0
	v_cmp_gt_i32_e64 s[86:87], v173, v0
	v_cmp_gt_i32_e64 s[88:89], v174, v0
	v_cmp_gt_i32_e64 s[90:91], v175, v0
	s_branch .LBB0_977
